# mix-in GEMM epilogue: the per-row-group s_waitcnt vmcnt(0) before the lower-bound values are used became counted waits vmcnt(g), so a group no longer waits for the previous group's store
# speedup vs baseline: 1.0027x; 1.0014x over previous
.LBB0_708:
	v_mad_i64_i32 v[134:135], s[6:7], v162, s34, 0
	v_lshl_add_u64 v[134:135], v[134:135], 1, s[20:21]
	v_cvt_pk_bf16_f32 v130, v138, v139
	v_lshl_add_u64 v[134:135], v[166:167], 1, v[134:135]
	v_cvt_pk_bf16_f32 v131, v140, v141
	v_cvt_pk_bf16_f32 v132, v142, v143
	v_cvt_pk_bf16_f32 v133, v144, v145
	global_store_dwordx4 v[134:135], v[130:133], off
	v_pk_mul_f32 v[126:127], v[126:127], v[174:175] op_sel:[0,1]
	v_pk_mul_f32 v[128:129], v[128:129], v[174:175] op_sel:[0,1]
	v_cndmask_b32_e64 v130, 0, 1, s[4:5]
	v_pk_mul_f32 v[122:123], v[122:123], v[174:175] op_sel:[0,1]
	v_pk_mul_f32 v[124:125], v[124:125], v[174:175] op_sel:[0,1]
	v_cmp_ne_u32_e64 s[42:43], 1, v130
	s_andn2_b64 vcc, exec, s[4:5]
	s_mov_b64 s[4:5], -1
	s_cbranch_vccnz .LBB0_712
	v_mov_b64_e32 v[136:137], v[124:125]
	v_mov_b64_e32 v[132:133], v[128:129]
	s_andn2_b64 vcc, exec, s[0:1]
	v_mov_b64_e32 v[134:135], v[122:123]
	v_mov_b64_e32 v[130:131], v[126:127]
	s_cbranch_vccnz .LBB0_711
	v_mul_f32_e32 v131, 0x3fb8aa3b, v122
	v_mul_f32_e32 v132, 0x3fb8aa3b, v127
	v_exp_f32_e32 v131, v131
	v_exp_f32_e32 v132, v132
	v_mul_f32_e32 v133, 0x3fb8aa3b, v128
	v_exp_f32_e32 v133, v133
	v_add_f32_e32 v131, 1.0, v131
	v_rcp_f32_e32 v134, v131
	v_add_f32_e32 v131, 1.0, v132
	v_mul_f32_e32 v132, 0x3fb8aa3b, v123
	v_exp_f32_e32 v132, v132
	v_mul_f32_e32 v136, 0x3fb8aa3b, v129
	v_exp_f32_e32 v137, v136
	v_mul_f32_e32 v130, 0x3fb8aa3b, v126
	v_add_f32_e32 v132, 1.0, v132
	v_rcp_f32_e32 v135, v132
	v_add_f32_e32 v132, 1.0, v133
	v_mul_f32_e32 v133, 0x3fb8aa3b, v124
	v_exp_f32_e32 v133, v133
	v_exp_f32_e32 v130, v130
	v_rcp_f32_e32 v131, v131
	v_rcp_f32_e32 v132, v132
	v_add_f32_e32 v133, 1.0, v133
	v_rcp_f32_e32 v136, v133
	v_add_f32_e32 v133, 1.0, v137
	v_mul_f32_e32 v137, 0x3fb8aa3b, v125
	v_exp_f32_e32 v137, v137
	v_add_f32_e32 v130, 1.0, v130
	v_rcp_f32_e32 v130, v130
	v_rcp_f32_e32 v133, v133
	v_add_f32_e32 v137, 1.0, v137
	v_rcp_f32_e32 v137, v137
	s_waitcnt vmcnt(1)
	v_sub_f32_e32 v139, 1.0, v103
	v_sub_f32_e32 v138, 1.0, v102
	v_sub_f32_e32 v141, 1.0, v105
	v_sub_f32_e32 v140, 1.0, v104
	v_pk_mul_f32 v[132:133], v[132:133], v[140:141]
	v_pk_mul_f32 v[130:131], v[130:131], v[138:139]
	v_sub_f32_e32 v139, 1.0, v99
	v_sub_f32_e32 v138, 1.0, v98
	v_sub_f32_e32 v141, 1.0, v101
	v_sub_f32_e32 v140, 1.0, v100
	v_pk_mul_f32 v[136:137], v[136:137], v[140:141]
	v_pk_mul_f32 v[134:135], v[134:135], v[138:139]

.LBB0_714:
	v_or_b32_e32 v126, 16, v162
	v_mad_i64_i32 v[126:127], s[4:5], v126, s34, 0
	v_lshl_add_u64 v[126:127], v[126:127], 1, s[20:21]
	v_cvt_pk_bf16_f32 v122, v130, v131
	v_cvt_pk_bf16_f32 v123, v132, v133
	v_cvt_pk_bf16_f32 v124, v134, v135
	v_cvt_pk_bf16_f32 v125, v136, v137
	v_lshl_add_u64 v[126:127], v[166:167], 1, v[126:127]
	v_pk_mul_f32 v[118:119], v[118:119], v[172:173] op_sel_hi:[1,0]
	v_pk_mul_f32 v[120:121], v[120:121], v[172:173] op_sel_hi:[1,0]
	v_pk_mul_f32 v[114:115], v[114:115], v[172:173] op_sel_hi:[1,0]
	v_pk_mul_f32 v[116:117], v[116:117], v[172:173] op_sel_hi:[1,0]
	s_and_b64 vcc, exec, s[42:43]
	s_mov_b64 s[4:5], -1
	global_store_dwordx4 v[126:127], v[122:125], off
	s_cbranch_vccnz .LBB0_718
	v_mov_b64_e32 v[128:129], v[116:117]
	v_mov_b64_e32 v[124:125], v[120:121]
	s_andn2_b64 vcc, exec, s[0:1]
	v_mov_b64_e32 v[126:127], v[114:115]
	v_mov_b64_e32 v[122:123], v[118:119]
	s_cbranch_vccnz .LBB0_717
	v_mul_f32_e32 v123, 0x3fb8aa3b, v114
	v_mul_f32_e32 v124, 0x3fb8aa3b, v119
	v_exp_f32_e32 v123, v123
	v_exp_f32_e32 v124, v124
	v_mul_f32_e32 v125, 0x3fb8aa3b, v120
	v_exp_f32_e32 v125, v125
	v_add_f32_e32 v123, 1.0, v123
	v_rcp_f32_e32 v126, v123
	v_add_f32_e32 v123, 1.0, v124
	v_mul_f32_e32 v124, 0x3fb8aa3b, v115
	v_exp_f32_e32 v124, v124
	v_mul_f32_e32 v128, 0x3fb8aa3b, v121
	v_exp_f32_e32 v129, v128
	v_mul_f32_e32 v122, 0x3fb8aa3b, v118
	v_add_f32_e32 v124, 1.0, v124
	v_rcp_f32_e32 v127, v124
	v_add_f32_e32 v124, 1.0, v125
	v_mul_f32_e32 v125, 0x3fb8aa3b, v116
	v_exp_f32_e32 v125, v125
	v_exp_f32_e32 v122, v122
	v_rcp_f32_e32 v123, v123
	v_rcp_f32_e32 v124, v124
	v_add_f32_e32 v125, 1.0, v125
	v_rcp_f32_e32 v128, v125
	v_add_f32_e32 v125, 1.0, v129
	v_mul_f32_e32 v129, 0x3fb8aa3b, v117
	v_exp_f32_e32 v129, v129
	v_add_f32_e32 v122, 1.0, v122
	v_rcp_f32_e32 v122, v122
	v_rcp_f32_e32 v125, v125
	v_add_f32_e32 v129, 1.0, v129
	v_rcp_f32_e32 v129, v129
	s_waitcnt vmcnt(2)
	v_sub_f32_e32 v131, 1.0, v103
	v_sub_f32_e32 v130, 1.0, v102
	v_sub_f32_e32 v133, 1.0, v105
	v_sub_f32_e32 v132, 1.0, v104
	v_pk_mul_f32 v[124:125], v[124:125], v[132:133]
	v_pk_mul_f32 v[122:123], v[122:123], v[130:131]
	v_sub_f32_e32 v131, 1.0, v99
	v_sub_f32_e32 v130, 1.0, v98
	v_sub_f32_e32 v133, 1.0, v101
	v_sub_f32_e32 v132, 1.0, v100
	v_pk_mul_f32 v[128:129], v[128:129], v[132:133]
	v_pk_mul_f32 v[126:127], v[126:127], v[130:131]

.LBB0_720:
	v_or_b32_e32 v118, 32, v162
	v_mad_i64_i32 v[118:119], s[4:5], v118, s34, 0
	v_lshl_add_u64 v[118:119], v[118:119], 1, s[20:21]
	v_cvt_pk_bf16_f32 v114, v122, v123
	v_cvt_pk_bf16_f32 v115, v124, v125
	v_cvt_pk_bf16_f32 v116, v126, v127
	v_cvt_pk_bf16_f32 v117, v128, v129
	v_lshl_add_u64 v[118:119], v[166:167], 1, v[118:119]
	v_pk_mul_f32 v[110:111], v[110:111], v[172:173] op_sel:[0,1]
	v_pk_mul_f32 v[112:113], v[112:113], v[172:173] op_sel:[0,1]
	v_pk_mul_f32 v[106:107], v[106:107], v[172:173] op_sel:[0,1]
	v_pk_mul_f32 v[108:109], v[108:109], v[172:173] op_sel:[0,1]
	s_and_b64 vcc, exec, s[42:43]
	s_mov_b64 s[4:5], -1
	global_store_dwordx4 v[118:119], v[114:117], off
	s_cbranch_vccnz .LBB0_724
	v_mov_b64_e32 v[120:121], v[108:109]
	v_mov_b64_e32 v[116:117], v[112:113]
	s_andn2_b64 vcc, exec, s[0:1]
	v_mov_b64_e32 v[118:119], v[106:107]
	v_mov_b64_e32 v[114:115], v[110:111]
	s_cbranch_vccnz .LBB0_723
	v_mul_f32_e32 v115, 0x3fb8aa3b, v106
	v_mul_f32_e32 v116, 0x3fb8aa3b, v111
	v_exp_f32_e32 v115, v115
	v_exp_f32_e32 v116, v116
	v_mul_f32_e32 v117, 0x3fb8aa3b, v112
	v_exp_f32_e32 v117, v117
	v_add_f32_e32 v115, 1.0, v115
	v_rcp_f32_e32 v118, v115
	v_add_f32_e32 v115, 1.0, v116
	v_mul_f32_e32 v116, 0x3fb8aa3b, v107
	v_exp_f32_e32 v116, v116
	v_mul_f32_e32 v120, 0x3fb8aa3b, v113
	v_exp_f32_e32 v121, v120
	v_mul_f32_e32 v114, 0x3fb8aa3b, v110
	v_add_f32_e32 v116, 1.0, v116
	v_rcp_f32_e32 v119, v116
	v_add_f32_e32 v116, 1.0, v117
	v_mul_f32_e32 v117, 0x3fb8aa3b, v108
	v_exp_f32_e32 v117, v117
	v_exp_f32_e32 v114, v114
	v_rcp_f32_e32 v115, v115
	v_rcp_f32_e32 v116, v116
	v_add_f32_e32 v117, 1.0, v117
	v_rcp_f32_e32 v120, v117
	v_add_f32_e32 v117, 1.0, v121
	v_mul_f32_e32 v121, 0x3fb8aa3b, v109
	v_exp_f32_e32 v121, v121
	v_add_f32_e32 v114, 1.0, v114
	v_rcp_f32_e32 v114, v114
	v_rcp_f32_e32 v117, v117
	v_add_f32_e32 v121, 1.0, v121
	v_rcp_f32_e32 v121, v121
	s_waitcnt vmcnt(3)
	v_sub_f32_e32 v123, 1.0, v103
	v_sub_f32_e32 v122, 1.0, v102
	v_sub_f32_e32 v125, 1.0, v105
	v_sub_f32_e32 v124, 1.0, v104
	v_pk_mul_f32 v[116:117], v[116:117], v[124:125]
	v_pk_mul_f32 v[114:115], v[114:115], v[122:123]
	v_sub_f32_e32 v123, 1.0, v99
	v_sub_f32_e32 v122, 1.0, v98
	v_sub_f32_e32 v125, 1.0, v101
	v_sub_f32_e32 v124, 1.0, v100
	v_pk_mul_f32 v[120:121], v[120:121], v[124:125]
	v_pk_mul_f32 v[118:119], v[118:119], v[122:123]

.LBB0_726:
	v_or_b32_e32 v110, 48, v162
	v_mad_i64_i32 v[110:111], s[4:5], v110, s34, 0
	v_lshl_add_u64 v[110:111], v[110:111], 1, s[20:21]
	v_cvt_pk_bf16_f32 v106, v114, v115
	v_cvt_pk_bf16_f32 v107, v116, v117
	v_cvt_pk_bf16_f32 v108, v118, v119
	v_cvt_pk_bf16_f32 v109, v120, v121
	v_lshl_add_u64 v[110:111], v[166:167], 1, v[110:111]
	v_pk_mul_f32 v[94:95], v[94:95], v[170:171] op_sel_hi:[1,0]
	v_pk_mul_f32 v[96:97], v[96:97], v[170:171] op_sel_hi:[1,0]
	v_pk_mul_f32 v[90:91], v[90:91], v[170:171] op_sel_hi:[1,0]
	v_pk_mul_f32 v[92:93], v[92:93], v[170:171] op_sel_hi:[1,0]
	s_and_b64 vcc, exec, s[42:43]
	s_mov_b64 s[4:5], -1
	global_store_dwordx4 v[110:111], v[106:109], off
	s_cbranch_vccnz .LBB0_730
	v_mov_b64_e32 v[112:113], v[92:93]
	v_mov_b64_e32 v[108:109], v[96:97]
	s_andn2_b64 vcc, exec, s[0:1]
	v_mov_b64_e32 v[110:111], v[90:91]
	v_mov_b64_e32 v[106:107], v[94:95]
	s_cbranch_vccnz .LBB0_729
	v_mul_f32_e32 v107, 0x3fb8aa3b, v90
	v_mul_f32_e32 v108, 0x3fb8aa3b, v95
	v_exp_f32_e32 v107, v107
	v_exp_f32_e32 v108, v108
	v_mul_f32_e32 v109, 0x3fb8aa3b, v96
	v_exp_f32_e32 v109, v109
	v_add_f32_e32 v107, 1.0, v107
	v_rcp_f32_e32 v110, v107
	v_add_f32_e32 v107, 1.0, v108
	v_mul_f32_e32 v108, 0x3fb8aa3b, v91
	v_exp_f32_e32 v108, v108
	v_mul_f32_e32 v112, 0x3fb8aa3b, v97
	v_exp_f32_e32 v113, v112
	v_mul_f32_e32 v106, 0x3fb8aa3b, v94
	v_add_f32_e32 v108, 1.0, v108
	v_rcp_f32_e32 v111, v108
	v_add_f32_e32 v108, 1.0, v109
	v_mul_f32_e32 v109, 0x3fb8aa3b, v92
	v_exp_f32_e32 v109, v109
	v_exp_f32_e32 v106, v106
	v_rcp_f32_e32 v107, v107
	v_rcp_f32_e32 v108, v108
	v_add_f32_e32 v109, 1.0, v109
	v_rcp_f32_e32 v112, v109
	v_add_f32_e32 v109, 1.0, v113
	v_mul_f32_e32 v113, 0x3fb8aa3b, v93
	v_exp_f32_e32 v113, v113
	v_add_f32_e32 v106, 1.0, v106
	v_rcp_f32_e32 v106, v106
	v_rcp_f32_e32 v109, v109
	v_add_f32_e32 v113, 1.0, v113
	v_rcp_f32_e32 v113, v113
	s_waitcnt vmcnt(4)
	v_sub_f32_e32 v115, 1.0, v103
	v_sub_f32_e32 v114, 1.0, v102
	v_sub_f32_e32 v117, 1.0, v105
	v_sub_f32_e32 v116, 1.0, v104
	v_pk_mul_f32 v[108:109], v[108:109], v[116:117]
	v_pk_mul_f32 v[106:107], v[106:107], v[114:115]
	v_sub_f32_e32 v115, 1.0, v99
	v_sub_f32_e32 v114, 1.0, v98
	v_sub_f32_e32 v117, 1.0, v101
	v_sub_f32_e32 v116, 1.0, v100
	v_pk_mul_f32 v[112:113], v[112:113], v[116:117]
	v_pk_mul_f32 v[110:111], v[110:111], v[114:115]

.LBB0_732:
	v_add_u32_e32 v94, 0x80, v162
	v_mad_i64_i32 v[94:95], s[4:5], v94, s34, 0
	v_lshl_add_u64 v[94:95], v[94:95], 1, s[20:21]
	v_cvt_pk_bf16_f32 v90, v106, v107
	v_cvt_pk_bf16_f32 v91, v108, v109
	v_cvt_pk_bf16_f32 v92, v110, v111
	v_cvt_pk_bf16_f32 v93, v112, v113
	v_lshl_add_u64 v[94:95], v[166:167], 1, v[94:95]
	v_pk_mul_f32 v[86:87], v[86:87], v[170:171] op_sel:[0,1]
	v_pk_mul_f32 v[88:89], v[88:89], v[170:171] op_sel:[0,1]
	v_pk_mul_f32 v[82:83], v[82:83], v[170:171] op_sel:[0,1]
	v_pk_mul_f32 v[84:85], v[84:85], v[170:171] op_sel:[0,1]
	s_and_b64 vcc, exec, s[42:43]
	s_mov_b64 s[4:5], -1
	global_store_dwordx4 v[94:95], v[90:93], off
	s_cbranch_vccnz .LBB0_736
	v_mov_b64_e32 v[96:97], v[84:85]
	v_mov_b64_e32 v[92:93], v[88:89]
	s_andn2_b64 vcc, exec, s[0:1]
	v_mov_b64_e32 v[94:95], v[82:83]
	v_mov_b64_e32 v[90:91], v[86:87]
	s_cbranch_vccnz .LBB0_735
	v_mul_f32_e32 v91, 0x3fb8aa3b, v82
	v_mul_f32_e32 v92, 0x3fb8aa3b, v87
	v_exp_f32_e32 v91, v91
	v_exp_f32_e32 v92, v92
	v_mul_f32_e32 v93, 0x3fb8aa3b, v88
	v_exp_f32_e32 v93, v93
	v_add_f32_e32 v91, 1.0, v91
	v_rcp_f32_e32 v94, v91
	v_add_f32_e32 v91, 1.0, v92
	v_mul_f32_e32 v92, 0x3fb8aa3b, v83
	v_exp_f32_e32 v92, v92
	v_mul_f32_e32 v96, 0x3fb8aa3b, v89
	v_exp_f32_e32 v97, v96
	v_mul_f32_e32 v90, 0x3fb8aa3b, v86
	v_add_f32_e32 v92, 1.0, v92
	v_rcp_f32_e32 v95, v92
	v_add_f32_e32 v92, 1.0, v93
	v_mul_f32_e32 v93, 0x3fb8aa3b, v84
	v_exp_f32_e32 v93, v93
	v_exp_f32_e32 v90, v90
	v_rcp_f32_e32 v91, v91
	v_rcp_f32_e32 v92, v92
	v_add_f32_e32 v93, 1.0, v93
	v_rcp_f32_e32 v96, v93
	v_add_f32_e32 v93, 1.0, v97
	v_mul_f32_e32 v97, 0x3fb8aa3b, v85
	v_exp_f32_e32 v97, v97
	v_add_f32_e32 v90, 1.0, v90
	v_rcp_f32_e32 v90, v90
	v_rcp_f32_e32 v93, v93
	v_add_f32_e32 v97, 1.0, v97
	v_rcp_f32_e32 v97, v97
	s_waitcnt vmcnt(5)
	v_sub_f32_e32 v107, 1.0, v103
	v_sub_f32_e32 v106, 1.0, v102
	v_sub_f32_e32 v109, 1.0, v105
	v_sub_f32_e32 v108, 1.0, v104
	v_pk_mul_f32 v[92:93], v[92:93], v[108:109]
	v_pk_mul_f32 v[90:91], v[90:91], v[106:107]
	v_sub_f32_e32 v107, 1.0, v99
	v_sub_f32_e32 v106, 1.0, v98
	v_sub_f32_e32 v109, 1.0, v101
	v_sub_f32_e32 v108, 1.0, v100
	v_pk_mul_f32 v[96:97], v[96:97], v[108:109]
	v_pk_mul_f32 v[94:95], v[94:95], v[106:107]

.LBB0_738:
	v_add_u32_e32 v86, 0x90, v162
	v_mad_i64_i32 v[86:87], s[4:5], v86, s34, 0
	v_lshl_add_u64 v[86:87], v[86:87], 1, s[20:21]
	v_cvt_pk_bf16_f32 v82, v90, v91
	v_cvt_pk_bf16_f32 v83, v92, v93
	v_cvt_pk_bf16_f32 v84, v94, v95
	v_cvt_pk_bf16_f32 v85, v96, v97
	v_lshl_add_u64 v[86:87], v[166:167], 1, v[86:87]
	v_pk_mul_f32 v[78:79], v[78:79], v[168:169] op_sel_hi:[1,0]
	v_pk_mul_f32 v[80:81], v[80:81], v[168:169] op_sel_hi:[1,0]
	v_pk_mul_f32 v[74:75], v[74:75], v[168:169] op_sel_hi:[1,0]
	v_pk_mul_f32 v[76:77], v[76:77], v[168:169] op_sel_hi:[1,0]
	s_and_b64 vcc, exec, s[42:43]
	s_mov_b64 s[4:5], -1
	global_store_dwordx4 v[86:87], v[82:85], off
	s_cbranch_vccnz .LBB0_742
	v_mov_b64_e32 v[88:89], v[76:77]
	v_mov_b64_e32 v[84:85], v[80:81]
	s_andn2_b64 vcc, exec, s[0:1]
	v_mov_b64_e32 v[86:87], v[74:75]
	v_mov_b64_e32 v[82:83], v[78:79]
	s_cbranch_vccnz .LBB0_741
	v_mul_f32_e32 v83, 0x3fb8aa3b, v74
	v_mul_f32_e32 v84, 0x3fb8aa3b, v79
	v_exp_f32_e32 v83, v83
	v_exp_f32_e32 v84, v84
	v_mul_f32_e32 v85, 0x3fb8aa3b, v80
	v_exp_f32_e32 v85, v85
	v_add_f32_e32 v83, 1.0, v83
	v_rcp_f32_e32 v86, v83
	v_add_f32_e32 v83, 1.0, v84
	v_mul_f32_e32 v84, 0x3fb8aa3b, v75
	v_exp_f32_e32 v84, v84
	v_mul_f32_e32 v88, 0x3fb8aa3b, v81
	v_exp_f32_e32 v89, v88
	v_mul_f32_e32 v82, 0x3fb8aa3b, v78
	v_add_f32_e32 v84, 1.0, v84
	v_rcp_f32_e32 v87, v84
	v_add_f32_e32 v84, 1.0, v85
	v_mul_f32_e32 v85, 0x3fb8aa3b, v76
	v_exp_f32_e32 v85, v85
	v_exp_f32_e32 v82, v82
	v_rcp_f32_e32 v83, v83
	v_rcp_f32_e32 v84, v84
	v_add_f32_e32 v85, 1.0, v85
	v_rcp_f32_e32 v88, v85
	v_add_f32_e32 v85, 1.0, v89
	v_mul_f32_e32 v89, 0x3fb8aa3b, v77
	v_exp_f32_e32 v89, v89
	v_add_f32_e32 v82, 1.0, v82
	v_rcp_f32_e32 v82, v82
	v_rcp_f32_e32 v85, v85
	v_add_f32_e32 v89, 1.0, v89
	v_rcp_f32_e32 v89, v89
	s_waitcnt vmcnt(6)
	v_sub_f32_e32 v91, 1.0, v103
	v_sub_f32_e32 v90, 1.0, v102
	v_sub_f32_e32 v93, 1.0, v105
	v_sub_f32_e32 v92, 1.0, v104
	v_pk_mul_f32 v[84:85], v[84:85], v[92:93]
	v_pk_mul_f32 v[82:83], v[82:83], v[90:91]
	v_sub_f32_e32 v91, 1.0, v99
	v_sub_f32_e32 v90, 1.0, v98
	v_sub_f32_e32 v93, 1.0, v101
	v_sub_f32_e32 v92, 1.0, v100
	v_pk_mul_f32 v[88:89], v[88:89], v[92:93]
	v_pk_mul_f32 v[86:87], v[86:87], v[90:91]

.LBB0_744:
	v_add_u32_e32 v78, 0xa0, v162
	v_mad_i64_i32 v[78:79], s[4:5], v78, s34, 0
	v_lshl_add_u64 v[78:79], v[78:79], 1, s[20:21]
	v_cvt_pk_bf16_f32 v74, v82, v83
	v_cvt_pk_bf16_f32 v75, v84, v85
	v_cvt_pk_bf16_f32 v76, v86, v87
	v_cvt_pk_bf16_f32 v77, v88, v89
	v_lshl_add_u64 v[78:79], v[166:167], 1, v[78:79]
	v_pk_mul_f32 v[70:71], v[70:71], v[168:169] op_sel:[0,1]
	v_pk_mul_f32 v[72:73], v[72:73], v[168:169] op_sel:[0,1]
	v_pk_mul_f32 v[66:67], v[66:67], v[168:169] op_sel:[0,1]
	v_pk_mul_f32 v[68:69], v[68:69], v[168:169] op_sel:[0,1]
	s_and_b64 vcc, exec, s[42:43]
	s_mov_b64 s[4:5], -1
	s_mov_b64 s[42:43], s[90:91]
	global_store_dwordx4 v[78:79], v[74:77], off
	s_cbranch_vccnz .LBB0_748
	v_mov_b64_e32 v[80:81], v[68:69]
	v_mov_b64_e32 v[76:77], v[72:73]
	s_andn2_b64 vcc, exec, s[0:1]
	v_mov_b64_e32 v[78:79], v[66:67]
	v_mov_b64_e32 v[74:75], v[70:71]
	s_cbranch_vccnz .LBB0_747
	v_mul_f32_e32 v75, 0x3fb8aa3b, v66
	v_mul_f32_e32 v76, 0x3fb8aa3b, v67
	v_mul_f32_e32 v77, 0x3fb8aa3b, v68
	v_exp_f32_e32 v75, v75
	v_exp_f32_e32 v76, v76
	v_exp_f32_e32 v77, v77
	v_mul_f32_e32 v74, 0x3fb8aa3b, v70
	v_add_f32_e32 v75, 1.0, v75
	v_add_f32_e32 v76, 1.0, v76
	v_add_f32_e32 v77, 1.0, v77
	v_rcp_f32_e32 v78, v75
	v_mul_f32_e32 v75, 0x3fb8aa3b, v71
	v_rcp_f32_e32 v79, v76
	v_mul_f32_e32 v76, 0x3fb8aa3b, v72
	v_rcp_f32_e32 v80, v77
	v_mul_f32_e32 v77, 0x3fb8aa3b, v73
	v_exp_f32_e32 v74, v74
	v_exp_f32_e32 v75, v75
	v_exp_f32_e32 v76, v76
	v_exp_f32_e32 v77, v77
	v_mul_f32_e32 v81, 0x3fb8aa3b, v69
	v_exp_f32_e32 v81, v81
	v_add_f32_e32 v74, 1.0, v74
	v_add_f32_e32 v75, 1.0, v75
	v_add_f32_e32 v76, 1.0, v76
	v_add_f32_e32 v77, 1.0, v77
	v_rcp_f32_e32 v74, v74
	v_rcp_f32_e32 v75, v75
	v_rcp_f32_e32 v76, v76
	v_rcp_f32_e32 v77, v77
	v_add_f32_e32 v81, 1.0, v81
	v_rcp_f32_e32 v81, v81
	s_waitcnt vmcnt(7)
	v_sub_f32_e32 v83, 1.0, v103
	v_sub_f32_e32 v82, 1.0, v102
	v_sub_f32_e32 v85, 1.0, v105
	v_sub_f32_e32 v84, 1.0, v104
	v_pk_mul_f32 v[76:77], v[76:77], v[84:85]
	v_pk_mul_f32 v[74:75], v[74:75], v[82:83]
	v_sub_f32_e32 v83, 1.0, v99
	v_sub_f32_e32 v82, 1.0, v98
	v_sub_f32_e32 v85, 1.0, v101
	v_sub_f32_e32 v84, 1.0, v100
	v_pk_mul_f32 v[80:81], v[80:81], v[84:85]
	v_pk_mul_f32 v[78:79], v[78:79], v[82:83]

.LBB0_764:
	v_mad_i64_i32 v[62:63], s[6:7], v162, s34, 0
	v_lshl_add_u64 v[62:63], v[62:63], 1, s[20:21]
	v_cvt_pk_bf16_f32 v58, v74, v75
	v_lshl_add_u64 v[62:63], v[166:167], 1, v[62:63]
	s_xor_b64 s[4:5], s[4:5], -1
	v_cvt_pk_bf16_f32 v59, v76, v77
	v_cvt_pk_bf16_f32 v60, v78, v79
	v_cvt_pk_bf16_f32 v61, v80, v81
	global_store_dwordx4 v[62:63], v[58:61], off offset:256
	v_pk_mul_f32 v[54:55], v[54:55], v[174:175] op_sel:[0,1]
	v_pk_mul_f32 v[56:57], v[56:57], v[174:175] op_sel:[0,1]
	v_cndmask_b32_e64 v58, 0, 1, s[4:5]
	v_pk_mul_f32 v[50:51], v[50:51], v[174:175] op_sel:[0,1]
	v_pk_mul_f32 v[52:53], v[52:53], v[174:175] op_sel:[0,1]
	v_cmp_ne_u32_e64 s[40:41], 1, v58
	s_andn2_b64 vcc, exec, s[4:5]
	s_mov_b64 s[4:5], -1
	s_cbranch_vccnz .LBB0_768
	v_mov_b64_e32 v[64:65], v[52:53]
	v_mov_b64_e32 v[60:61], v[56:57]
	s_andn2_b64 vcc, exec, s[0:1]
	v_mov_b64_e32 v[62:63], v[50:51]
	v_mov_b64_e32 v[58:59], v[54:55]
	s_cbranch_vccnz .LBB0_767
	v_mul_f32_e32 v59, 0x3fb8aa3b, v50
	v_mul_f32_e32 v60, 0x3fb8aa3b, v55
	v_exp_f32_e32 v59, v59
	v_exp_f32_e32 v60, v60
	v_mul_f32_e32 v61, 0x3fb8aa3b, v56
	v_exp_f32_e32 v61, v61
	v_add_f32_e32 v59, 1.0, v59
	v_rcp_f32_e32 v62, v59
	v_add_f32_e32 v59, 1.0, v60
	v_mul_f32_e32 v60, 0x3fb8aa3b, v51
	v_exp_f32_e32 v60, v60
	v_mul_f32_e32 v64, 0x3fb8aa3b, v57
	v_exp_f32_e32 v65, v64
	v_mul_f32_e32 v58, 0x3fb8aa3b, v54
	v_add_f32_e32 v60, 1.0, v60
	v_rcp_f32_e32 v63, v60
	v_add_f32_e32 v60, 1.0, v61
	v_mul_f32_e32 v61, 0x3fb8aa3b, v52
	v_exp_f32_e32 v61, v61
	v_exp_f32_e32 v58, v58
	v_rcp_f32_e32 v59, v59
	v_rcp_f32_e32 v60, v60
	v_add_f32_e32 v61, 1.0, v61
	v_rcp_f32_e32 v64, v61
	v_add_f32_e32 v61, 1.0, v65
	v_mul_f32_e32 v65, 0x3fb8aa3b, v53
	v_exp_f32_e32 v65, v65
	v_add_f32_e32 v58, 1.0, v58
	v_rcp_f32_e32 v58, v58
	v_rcp_f32_e32 v61, v61
	v_add_f32_e32 v65, 1.0, v65
	v_rcp_f32_e32 v65, v65
	s_waitcnt vmcnt(1)
	v_sub_f32_e32 v75, 1.0, v71
	v_sub_f32_e32 v74, 1.0, v70
	v_sub_f32_e32 v77, 1.0, v73
	v_sub_f32_e32 v76, 1.0, v72
	v_pk_mul_f32 v[60:61], v[60:61], v[76:77]
	v_pk_mul_f32 v[58:59], v[58:59], v[74:75]
	v_sub_f32_e32 v75, 1.0, v67
	v_sub_f32_e32 v74, 1.0, v66
	v_sub_f32_e32 v77, 1.0, v69
	v_sub_f32_e32 v76, 1.0, v68
	v_pk_mul_f32 v[64:65], v[64:65], v[76:77]
	v_pk_mul_f32 v[62:63], v[62:63], v[74:75]

.LBB0_770:
	v_or_b32_e32 v54, 16, v162
	v_mad_i64_i32 v[54:55], s[4:5], v54, s34, 0
	v_lshl_add_u64 v[54:55], v[54:55], 1, s[20:21]
	v_cvt_pk_bf16_f32 v50, v58, v59
	v_cvt_pk_bf16_f32 v51, v60, v61
	v_cvt_pk_bf16_f32 v52, v62, v63
	v_cvt_pk_bf16_f32 v53, v64, v65
	v_lshl_add_u64 v[54:55], v[166:167], 1, v[54:55]
	v_pk_mul_f32 v[46:47], v[46:47], v[172:173] op_sel_hi:[1,0]
	v_pk_mul_f32 v[48:49], v[48:49], v[172:173] op_sel_hi:[1,0]
	v_pk_mul_f32 v[42:43], v[42:43], v[172:173] op_sel_hi:[1,0]
	v_pk_mul_f32 v[44:45], v[44:45], v[172:173] op_sel_hi:[1,0]
	s_and_b64 vcc, exec, s[40:41]
	s_mov_b64 s[4:5], -1
	global_store_dwordx4 v[54:55], v[50:53], off offset:256
	s_cbranch_vccnz .LBB0_774
	v_mov_b64_e32 v[56:57], v[44:45]
	v_mov_b64_e32 v[52:53], v[48:49]
	s_andn2_b64 vcc, exec, s[0:1]
	v_mov_b64_e32 v[54:55], v[42:43]
	v_mov_b64_e32 v[50:51], v[46:47]
	s_cbranch_vccnz .LBB0_773
	v_mul_f32_e32 v51, 0x3fb8aa3b, v42
	v_mul_f32_e32 v52, 0x3fb8aa3b, v47
	v_exp_f32_e32 v51, v51
	v_exp_f32_e32 v52, v52
	v_mul_f32_e32 v53, 0x3fb8aa3b, v48
	v_exp_f32_e32 v53, v53
	v_add_f32_e32 v51, 1.0, v51
	v_rcp_f32_e32 v54, v51
	v_add_f32_e32 v51, 1.0, v52
	v_mul_f32_e32 v52, 0x3fb8aa3b, v43
	v_exp_f32_e32 v52, v52
	v_mul_f32_e32 v56, 0x3fb8aa3b, v49
	v_exp_f32_e32 v57, v56
	v_mul_f32_e32 v50, 0x3fb8aa3b, v46
	v_add_f32_e32 v52, 1.0, v52
	v_rcp_f32_e32 v55, v52
	v_add_f32_e32 v52, 1.0, v53
	v_mul_f32_e32 v53, 0x3fb8aa3b, v44
	v_exp_f32_e32 v53, v53
	v_exp_f32_e32 v50, v50
	v_rcp_f32_e32 v51, v51
	v_rcp_f32_e32 v52, v52
	v_add_f32_e32 v53, 1.0, v53
	v_rcp_f32_e32 v56, v53
	v_add_f32_e32 v53, 1.0, v57
	v_mul_f32_e32 v57, 0x3fb8aa3b, v45
	v_exp_f32_e32 v57, v57
	v_add_f32_e32 v50, 1.0, v50
	v_rcp_f32_e32 v50, v50
	v_rcp_f32_e32 v53, v53
	v_add_f32_e32 v57, 1.0, v57
	v_rcp_f32_e32 v57, v57
	s_waitcnt vmcnt(2)
	v_sub_f32_e32 v59, 1.0, v71
	v_sub_f32_e32 v58, 1.0, v70
	v_sub_f32_e32 v61, 1.0, v73
	v_sub_f32_e32 v60, 1.0, v72
	v_pk_mul_f32 v[52:53], v[52:53], v[60:61]
	v_pk_mul_f32 v[50:51], v[50:51], v[58:59]
	v_sub_f32_e32 v59, 1.0, v67
	v_sub_f32_e32 v58, 1.0, v66
	v_sub_f32_e32 v61, 1.0, v69
	v_sub_f32_e32 v60, 1.0, v68
	v_pk_mul_f32 v[56:57], v[56:57], v[60:61]
	v_pk_mul_f32 v[54:55], v[54:55], v[58:59]

.LBB0_776:
	v_or_b32_e32 v46, 32, v162
	v_mad_i64_i32 v[46:47], s[4:5], v46, s34, 0
	v_lshl_add_u64 v[46:47], v[46:47], 1, s[20:21]
	v_cvt_pk_bf16_f32 v42, v50, v51
	v_cvt_pk_bf16_f32 v43, v52, v53
	v_cvt_pk_bf16_f32 v44, v54, v55
	v_cvt_pk_bf16_f32 v45, v56, v57
	v_lshl_add_u64 v[46:47], v[166:167], 1, v[46:47]
	v_pk_mul_f32 v[38:39], v[38:39], v[172:173] op_sel:[0,1]
	v_pk_mul_f32 v[40:41], v[40:41], v[172:173] op_sel:[0,1]
	v_pk_mul_f32 v[34:35], v[34:35], v[172:173] op_sel:[0,1]
	v_pk_mul_f32 v[36:37], v[36:37], v[172:173] op_sel:[0,1]
	s_and_b64 vcc, exec, s[40:41]
	s_mov_b64 s[4:5], -1
	global_store_dwordx4 v[46:47], v[42:45], off offset:256
	s_cbranch_vccnz .LBB0_780
	v_mov_b64_e32 v[48:49], v[36:37]
	v_mov_b64_e32 v[44:45], v[40:41]
	s_andn2_b64 vcc, exec, s[0:1]
	v_mov_b64_e32 v[46:47], v[34:35]
	v_mov_b64_e32 v[42:43], v[38:39]
	s_cbranch_vccnz .LBB0_779
	v_mul_f32_e32 v43, 0x3fb8aa3b, v34
	v_mul_f32_e32 v44, 0x3fb8aa3b, v39
	v_exp_f32_e32 v43, v43
	v_exp_f32_e32 v44, v44
	v_mul_f32_e32 v45, 0x3fb8aa3b, v40
	v_exp_f32_e32 v45, v45
	v_add_f32_e32 v43, 1.0, v43
	v_rcp_f32_e32 v46, v43
	v_add_f32_e32 v43, 1.0, v44
	v_mul_f32_e32 v44, 0x3fb8aa3b, v35
	v_exp_f32_e32 v44, v44
	v_mul_f32_e32 v48, 0x3fb8aa3b, v41
	v_exp_f32_e32 v49, v48
	v_mul_f32_e32 v42, 0x3fb8aa3b, v38
	v_add_f32_e32 v44, 1.0, v44
	v_rcp_f32_e32 v47, v44
	v_add_f32_e32 v44, 1.0, v45
	v_mul_f32_e32 v45, 0x3fb8aa3b, v36
	v_exp_f32_e32 v45, v45
	v_exp_f32_e32 v42, v42
	v_rcp_f32_e32 v43, v43
	v_rcp_f32_e32 v44, v44
	v_add_f32_e32 v45, 1.0, v45
	v_rcp_f32_e32 v48, v45
	v_add_f32_e32 v45, 1.0, v49
	v_mul_f32_e32 v49, 0x3fb8aa3b, v37
	v_exp_f32_e32 v49, v49
	v_add_f32_e32 v42, 1.0, v42
	v_rcp_f32_e32 v42, v42
	v_rcp_f32_e32 v45, v45
	v_add_f32_e32 v49, 1.0, v49
	v_rcp_f32_e32 v49, v49
	s_waitcnt vmcnt(3)
	v_sub_f32_e32 v51, 1.0, v71
	v_sub_f32_e32 v50, 1.0, v70
	v_sub_f32_e32 v53, 1.0, v73
	v_sub_f32_e32 v52, 1.0, v72
	v_pk_mul_f32 v[44:45], v[44:45], v[52:53]
	v_pk_mul_f32 v[42:43], v[42:43], v[50:51]
	v_sub_f32_e32 v51, 1.0, v67
	v_sub_f32_e32 v50, 1.0, v66
	v_sub_f32_e32 v53, 1.0, v69
	v_sub_f32_e32 v52, 1.0, v68
	v_pk_mul_f32 v[48:49], v[48:49], v[52:53]
	v_pk_mul_f32 v[46:47], v[46:47], v[50:51]

.LBB0_782:
	v_or_b32_e32 v38, 48, v162
	v_mad_i64_i32 v[38:39], s[4:5], v38, s34, 0
	v_lshl_add_u64 v[38:39], v[38:39], 1, s[20:21]
	v_cvt_pk_bf16_f32 v34, v42, v43
	v_cvt_pk_bf16_f32 v35, v44, v45
	v_cvt_pk_bf16_f32 v36, v46, v47
	v_cvt_pk_bf16_f32 v37, v48, v49
	v_lshl_add_u64 v[38:39], v[166:167], 1, v[38:39]
	v_pk_mul_f32 v[30:31], v[30:31], v[170:171] op_sel_hi:[1,0]
	v_pk_mul_f32 v[32:33], v[32:33], v[170:171] op_sel_hi:[1,0]
	v_pk_mul_f32 v[26:27], v[26:27], v[170:171] op_sel_hi:[1,0]
	v_pk_mul_f32 v[28:29], v[28:29], v[170:171] op_sel_hi:[1,0]
	s_and_b64 vcc, exec, s[40:41]
	s_mov_b64 s[4:5], -1
	global_store_dwordx4 v[38:39], v[34:37], off offset:256
	s_cbranch_vccnz .LBB0_786
	v_mov_b64_e32 v[40:41], v[28:29]
	v_mov_b64_e32 v[36:37], v[32:33]
	s_andn2_b64 vcc, exec, s[0:1]
	v_mov_b64_e32 v[38:39], v[26:27]
	v_mov_b64_e32 v[34:35], v[30:31]
	s_cbranch_vccnz .LBB0_785
	v_mul_f32_e32 v35, 0x3fb8aa3b, v26
	v_mul_f32_e32 v36, 0x3fb8aa3b, v31
	v_exp_f32_e32 v35, v35
	v_exp_f32_e32 v36, v36
	v_mul_f32_e32 v37, 0x3fb8aa3b, v32
	v_exp_f32_e32 v37, v37
	v_add_f32_e32 v35, 1.0, v35
	v_rcp_f32_e32 v38, v35
	v_add_f32_e32 v35, 1.0, v36
	v_mul_f32_e32 v36, 0x3fb8aa3b, v27
	v_exp_f32_e32 v36, v36
	v_mul_f32_e32 v40, 0x3fb8aa3b, v33
	v_exp_f32_e32 v41, v40
	v_mul_f32_e32 v34, 0x3fb8aa3b, v30
	v_add_f32_e32 v36, 1.0, v36
	v_rcp_f32_e32 v39, v36
	v_add_f32_e32 v36, 1.0, v37
	v_mul_f32_e32 v37, 0x3fb8aa3b, v28
	v_exp_f32_e32 v37, v37
	v_exp_f32_e32 v34, v34
	v_rcp_f32_e32 v35, v35
	v_rcp_f32_e32 v36, v36
	v_add_f32_e32 v37, 1.0, v37
	v_rcp_f32_e32 v40, v37
	v_add_f32_e32 v37, 1.0, v41
	v_mul_f32_e32 v41, 0x3fb8aa3b, v29
	v_exp_f32_e32 v41, v41
	v_add_f32_e32 v34, 1.0, v34
	v_rcp_f32_e32 v34, v34
	v_rcp_f32_e32 v37, v37
	v_add_f32_e32 v41, 1.0, v41
	v_rcp_f32_e32 v41, v41
	s_waitcnt vmcnt(4)
	v_sub_f32_e32 v43, 1.0, v71
	v_sub_f32_e32 v42, 1.0, v70
	v_sub_f32_e32 v45, 1.0, v73
	v_sub_f32_e32 v44, 1.0, v72
	v_pk_mul_f32 v[36:37], v[36:37], v[44:45]
	v_pk_mul_f32 v[34:35], v[34:35], v[42:43]
	v_sub_f32_e32 v43, 1.0, v67
	v_sub_f32_e32 v42, 1.0, v66
	v_sub_f32_e32 v45, 1.0, v69
	v_sub_f32_e32 v44, 1.0, v68
	v_pk_mul_f32 v[40:41], v[40:41], v[44:45]
	v_pk_mul_f32 v[38:39], v[38:39], v[42:43]

.LBB0_788:
	v_add_u32_e32 v30, 0x80, v162
	v_mad_i64_i32 v[30:31], s[4:5], v30, s34, 0
	v_lshl_add_u64 v[30:31], v[30:31], 1, s[20:21]
	v_cvt_pk_bf16_f32 v26, v34, v35
	v_cvt_pk_bf16_f32 v27, v36, v37
	v_cvt_pk_bf16_f32 v28, v38, v39
	v_cvt_pk_bf16_f32 v29, v40, v41
	v_lshl_add_u64 v[30:31], v[166:167], 1, v[30:31]
	v_pk_mul_f32 v[22:23], v[22:23], v[170:171] op_sel:[0,1]
	v_pk_mul_f32 v[24:25], v[24:25], v[170:171] op_sel:[0,1]
	v_pk_mul_f32 v[18:19], v[18:19], v[170:171] op_sel:[0,1]
	v_pk_mul_f32 v[20:21], v[20:21], v[170:171] op_sel:[0,1]
	s_and_b64 vcc, exec, s[40:41]
	s_mov_b64 s[4:5], -1
	global_store_dwordx4 v[30:31], v[26:29], off offset:256
	s_cbranch_vccnz .LBB0_792
	v_mov_b64_e32 v[32:33], v[20:21]
	v_mov_b64_e32 v[28:29], v[24:25]
	s_andn2_b64 vcc, exec, s[0:1]
	v_mov_b64_e32 v[30:31], v[18:19]
	v_mov_b64_e32 v[26:27], v[22:23]
	s_cbranch_vccnz .LBB0_791
	v_mul_f32_e32 v27, 0x3fb8aa3b, v18
	v_mul_f32_e32 v28, 0x3fb8aa3b, v23
	v_exp_f32_e32 v27, v27
	v_exp_f32_e32 v28, v28
	v_mul_f32_e32 v29, 0x3fb8aa3b, v24
	v_exp_f32_e32 v29, v29
	v_add_f32_e32 v27, 1.0, v27
	v_rcp_f32_e32 v30, v27
	v_add_f32_e32 v27, 1.0, v28
	v_mul_f32_e32 v28, 0x3fb8aa3b, v19
	v_exp_f32_e32 v28, v28
	v_mul_f32_e32 v32, 0x3fb8aa3b, v25
	v_exp_f32_e32 v33, v32
	v_mul_f32_e32 v26, 0x3fb8aa3b, v22
	v_add_f32_e32 v28, 1.0, v28
	v_rcp_f32_e32 v31, v28
	v_add_f32_e32 v28, 1.0, v29
	v_mul_f32_e32 v29, 0x3fb8aa3b, v20
	v_exp_f32_e32 v29, v29
	v_exp_f32_e32 v26, v26
	v_rcp_f32_e32 v27, v27
	v_rcp_f32_e32 v28, v28
	v_add_f32_e32 v29, 1.0, v29
	v_rcp_f32_e32 v32, v29
	v_add_f32_e32 v29, 1.0, v33
	v_mul_f32_e32 v33, 0x3fb8aa3b, v21
	v_exp_f32_e32 v33, v33
	v_add_f32_e32 v26, 1.0, v26
	v_rcp_f32_e32 v26, v26
	v_rcp_f32_e32 v29, v29
	v_add_f32_e32 v33, 1.0, v33
	v_rcp_f32_e32 v33, v33
	s_waitcnt vmcnt(5)
	v_sub_f32_e32 v35, 1.0, v71
	v_sub_f32_e32 v34, 1.0, v70
	v_sub_f32_e32 v37, 1.0, v73
	v_sub_f32_e32 v36, 1.0, v72
	v_pk_mul_f32 v[28:29], v[28:29], v[36:37]
	v_pk_mul_f32 v[26:27], v[26:27], v[34:35]
	v_sub_f32_e32 v35, 1.0, v67
	v_sub_f32_e32 v34, 1.0, v66
	v_sub_f32_e32 v37, 1.0, v69
	v_sub_f32_e32 v36, 1.0, v68
	v_pk_mul_f32 v[32:33], v[32:33], v[36:37]
	v_pk_mul_f32 v[30:31], v[30:31], v[34:35]

.LBB0_794:
	v_add_u32_e32 v22, 0x90, v162
	v_mad_i64_i32 v[22:23], s[4:5], v22, s34, 0
	v_lshl_add_u64 v[22:23], v[22:23], 1, s[20:21]
	v_cvt_pk_bf16_f32 v18, v26, v27
	v_cvt_pk_bf16_f32 v19, v28, v29
	v_cvt_pk_bf16_f32 v20, v30, v31
	v_cvt_pk_bf16_f32 v21, v32, v33
	v_lshl_add_u64 v[22:23], v[166:167], 1, v[22:23]
	v_pk_mul_f32 v[14:15], v[14:15], v[168:169] op_sel_hi:[1,0]
	v_pk_mul_f32 v[16:17], v[16:17], v[168:169] op_sel_hi:[1,0]
	v_pk_mul_f32 v[10:11], v[10:11], v[168:169] op_sel_hi:[1,0]
	v_pk_mul_f32 v[12:13], v[12:13], v[168:169] op_sel_hi:[1,0]
	s_and_b64 vcc, exec, s[40:41]
	s_mov_b64 s[4:5], -1
	global_store_dwordx4 v[22:23], v[18:21], off offset:256
	s_cbranch_vccnz .LBB0_798
	v_mov_b64_e32 v[24:25], v[12:13]
	v_mov_b64_e32 v[20:21], v[16:17]
	s_andn2_b64 vcc, exec, s[0:1]
	v_mov_b64_e32 v[22:23], v[10:11]
	v_mov_b64_e32 v[18:19], v[14:15]
	s_cbranch_vccnz .LBB0_797
	v_mul_f32_e32 v19, 0x3fb8aa3b, v10
	v_mul_f32_e32 v20, 0x3fb8aa3b, v15
	v_exp_f32_e32 v19, v19
	v_exp_f32_e32 v20, v20
	v_mul_f32_e32 v21, 0x3fb8aa3b, v16
	v_exp_f32_e32 v21, v21
	v_add_f32_e32 v19, 1.0, v19
	v_rcp_f32_e32 v22, v19
	v_add_f32_e32 v19, 1.0, v20
	v_mul_f32_e32 v20, 0x3fb8aa3b, v11
	v_exp_f32_e32 v20, v20
	v_mul_f32_e32 v24, 0x3fb8aa3b, v17
	v_exp_f32_e32 v25, v24
	v_mul_f32_e32 v18, 0x3fb8aa3b, v14
	v_add_f32_e32 v20, 1.0, v20
	v_rcp_f32_e32 v23, v20
	v_add_f32_e32 v20, 1.0, v21
	v_mul_f32_e32 v21, 0x3fb8aa3b, v12
	v_exp_f32_e32 v21, v21
	v_exp_f32_e32 v18, v18
	v_rcp_f32_e32 v19, v19
	v_rcp_f32_e32 v20, v20
	v_add_f32_e32 v21, 1.0, v21
	v_rcp_f32_e32 v24, v21
	v_add_f32_e32 v21, 1.0, v25
	v_mul_f32_e32 v25, 0x3fb8aa3b, v13
	v_exp_f32_e32 v25, v25
	v_add_f32_e32 v18, 1.0, v18
	v_rcp_f32_e32 v18, v18
	v_rcp_f32_e32 v21, v21
	v_add_f32_e32 v25, 1.0, v25
	v_rcp_f32_e32 v25, v25
	s_waitcnt vmcnt(6)
	v_sub_f32_e32 v27, 1.0, v71
	v_sub_f32_e32 v26, 1.0, v70
	v_sub_f32_e32 v29, 1.0, v73
	v_sub_f32_e32 v28, 1.0, v72
	v_pk_mul_f32 v[20:21], v[20:21], v[28:29]
	v_pk_mul_f32 v[18:19], v[18:19], v[26:27]
	v_sub_f32_e32 v27, 1.0, v67
	v_sub_f32_e32 v26, 1.0, v66
	v_sub_f32_e32 v29, 1.0, v69
	v_sub_f32_e32 v28, 1.0, v68
	v_pk_mul_f32 v[24:25], v[24:25], v[28:29]
	v_pk_mul_f32 v[22:23], v[22:23], v[26:27]

.LBB0_800:
	v_add_u32_e32 v14, 0xa0, v162
	v_mad_i64_i32 v[14:15], s[4:5], v14, s34, 0
	v_lshl_add_u64 v[14:15], v[14:15], 1, s[20:21]
	v_cvt_pk_bf16_f32 v10, v18, v19
	v_cvt_pk_bf16_f32 v11, v20, v21
	v_cvt_pk_bf16_f32 v12, v22, v23
	v_cvt_pk_bf16_f32 v13, v24, v25
	v_lshl_add_u64 v[14:15], v[166:167], 1, v[14:15]
	v_pk_mul_f32 v[6:7], v[6:7], v[168:169] op_sel:[0,1]
	v_pk_mul_f32 v[8:9], v[8:9], v[168:169] op_sel:[0,1]
	v_pk_mul_f32 v[2:3], v[2:3], v[168:169] op_sel:[0,1]
	v_pk_mul_f32 v[4:5], v[4:5], v[168:169] op_sel:[0,1]
	s_and_b64 vcc, exec, s[40:41]
	s_mov_b64 s[4:5], -1
	global_store_dwordx4 v[14:15], v[10:13], off offset:256
	s_cbranch_vccnz .LBB0_804
	v_mov_b64_e32 v[16:17], v[4:5]
	v_mov_b64_e32 v[12:13], v[8:9]
	s_andn2_b64 vcc, exec, s[0:1]
	v_mov_b64_e32 v[14:15], v[2:3]
	v_mov_b64_e32 v[10:11], v[6:7]
	s_cbranch_vccnz .LBB0_803
	v_mul_f32_e32 v11, 0x3fb8aa3b, v2
	v_mul_f32_e32 v12, 0x3fb8aa3b, v3
	v_mul_f32_e32 v13, 0x3fb8aa3b, v4
	v_exp_f32_e32 v11, v11
	v_exp_f32_e32 v12, v12
	v_exp_f32_e32 v13, v13
	v_mul_f32_e32 v10, 0x3fb8aa3b, v6
	v_add_f32_e32 v11, 1.0, v11
	v_add_f32_e32 v12, 1.0, v12
	v_add_f32_e32 v13, 1.0, v13
	v_rcp_f32_e32 v14, v11
	v_mul_f32_e32 v11, 0x3fb8aa3b, v7
	v_rcp_f32_e32 v15, v12
	v_mul_f32_e32 v12, 0x3fb8aa3b, v8
	v_rcp_f32_e32 v16, v13
	v_mul_f32_e32 v13, 0x3fb8aa3b, v9
	v_exp_f32_e32 v10, v10
	v_exp_f32_e32 v11, v11
	v_exp_f32_e32 v12, v12
	v_exp_f32_e32 v13, v13
	v_mul_f32_e32 v17, 0x3fb8aa3b, v5
	v_exp_f32_e32 v17, v17
	v_add_f32_e32 v10, 1.0, v10
	v_add_f32_e32 v11, 1.0, v11
	v_add_f32_e32 v12, 1.0, v12
	v_add_f32_e32 v13, 1.0, v13
	v_rcp_f32_e32 v10, v10
	v_rcp_f32_e32 v11, v11
	v_rcp_f32_e32 v12, v12
	v_rcp_f32_e32 v13, v13
	v_add_f32_e32 v17, 1.0, v17
	v_rcp_f32_e32 v17, v17
	s_waitcnt vmcnt(7)
	v_sub_f32_e32 v19, 1.0, v71
	v_sub_f32_e32 v18, 1.0, v70
	v_sub_f32_e32 v21, 1.0, v73
	v_sub_f32_e32 v20, 1.0, v72
	v_pk_mul_f32 v[12:13], v[12:13], v[20:21]
	v_pk_mul_f32 v[10:11], v[10:11], v[18:19]
	v_sub_f32_e32 v19, 1.0, v67
	v_sub_f32_e32 v18, 1.0, v66
	v_sub_f32_e32 v21, 1.0, v69
	v_sub_f32_e32 v20, 1.0, v68
	v_pk_mul_f32 v[16:17], v[16:17], v[20:21]
	v_pk_mul_f32 v[14:15], v[14:15], v[18:19]
